# hand-written EpiGlu epilogue (fewer f32 VALU ops: o=(g*u)*rcp(irs2*(1+exp2(g*c))), irs2 staged next to rstd; bpermute/store pipelined) on top of peeled K-loops
# speedup vs baseline: 1.0145x; 1.0073x over previous
.LBB0_319:
	v_mov_b32_e32 v142, v1
	v_mov_b32_e32 v143, v144
	s_lshl_b32 s23, s57, 8
	v_lshl_add_u32 v143, v143, 4, v142
	v_add_u32_e32 v147, s53, v143
	v_cmp_gt_i32_e32 vcc, s85, v147
	s_and_saveexec_b64 s[28:29], vcc
	s_cbranch_execz .LBB0_321
	v_lshlrev_b32_e32 v160, 6, v147
	v_add_u32_e32 v160, 0x20400, v160
	ds_read_b128 v[148:151], v160
	ds_read_b128 v[152:155], v160 offset:32
	ds_read_b128 v[156:159], v160 offset:16
	ds_read_b128 v[160:163], v160 offset:48
	s_mov_b32 s25, 0x800000
	v_lshl_add_u32 v147, v147, 2, v225
	s_waitcnt lgkmcnt(0)
	v_mov_b32_e32 v164, v148
	v_mov_b32_e32 v165, v152
	v_mov_b32_e32 v152, v149
	v_mov_b32_e32 v148, v150
	v_mov_b32_e32 v149, v154
	v_mov_b32_e32 v154, v151
	v_mov_b32_e32 v150, v156
	v_mov_b32_e32 v151, v160
	v_mov_b32_e32 v160, v157
	v_mov_b32_e32 v156, v158
	v_mov_b32_e32 v157, v162
	v_mov_b32_e32 v162, v159
	v_pk_add_f32 v[152:153], v[164:165], v[152:153]
	v_pk_add_f32 v[148:149], v[148:149], v[154:155]
	v_pk_add_f32 v[150:151], v[150:151], v[160:161]
	v_pk_add_f32 v[154:155], v[156:157], v[162:163]
	v_pk_add_f32 v[148:149], v[152:153], v[148:149]
	v_pk_add_f32 v[150:151], v[150:151], v[154:155]
	s_nop 0
	v_pk_add_f32 v[148:149], v[148:149], v[150:151]
	s_nop 0
	v_add_f32_e32 v148, v148, v149
	v_fmamk_f32 v148, v148, 0x3a800000, v223
	ds_write_b32 v147, v148 offset:17408
	v_mul_f32_e32 v149, 0x4b800000, v148
	v_cmp_gt_f32_e32 vcc, s25, v148
	s_nop 1
	v_cndmask_b32_e32 v148, v148, v149, vcc
	v_rsq_f32_e32 v148, v148
	s_nop 0
	v_mul_f32_e32 v149, 0x45800000, v148
	v_cndmask_b32_e32 v148, v148, v149, vcc
	ds_write_b32 v147, v148
.LBB0_321:
	s_or_b64 exec, exec, s[28:29]
	s_lshl_b32 s25, s56, 7
	v_and_b32_e32 v148, 3, v142
	s_or_b32 s25, s25, s50
	v_lshl_or_b32 v150, v148, 3, s25
	v_ashrrev_i32_e32 v147, 2, v143
	v_and_b32_e32 v143, -4, v143
	s_waitcnt lgkmcnt(0)
	s_barrier
	v_lshl_add_u32 v149, v142, 2, s54
	v_ashrrev_i32_e32 v151, 31, v150
	v_lshl_add_u32 v148, v148, 6, v143
	v_lshl_add_u64 v[142:143], v[150:151], 1, s[20:21]
	ds_read_b32 v160, v149
	ds_read_b32 v161, v149 offset:64
	ds_read_b32 v162, v149 offset:128
	ds_read_b32 v163, v149 offset:192
	ds_read_b32 v164, v149 offset:512
	ds_read_b32 v165, v149 offset:576
	ds_read_b32 v166, v149 offset:640
	ds_read_b32 v167, v149 offset:704
	ds_read_b32 v206, v149 offset:17408
	ds_read_b32 v208, v149 offset:17472
	ds_read_b32 v210, v149 offset:17536
	ds_read_b32 v212, v149 offset:17600
	ds_read_b32 v214, v149 offset:17920
	ds_read_b32 v216, v149 offset:17984
	ds_read_b32 v218, v149 offset:18048
	ds_read_b32 v220, v149 offset:18112
	s_add_i32 s23, s23, s49
	v_add_u32_e32 v147, s23, v147
	s_movk_i32 s23, 0x1600
	s_nop 0
	v_mad_i64_i32 v[192:193], s[28:29], v147, s23, v[142:143]
	s_mov_b32 s28, 0x16000
	s_mov_b32 s29, 0
	s_waitcnt lgkmcnt(0)
	v_mul_f32_e32 v170, 0xbfb8aa3b, v160
	v_mul_f32_e32 v172, 0xbfb8aa3b, v161
	v_mul_f32_e32 v174, 0xbfb8aa3b, v162
	v_mul_f32_e32 v176, 0xbfb8aa3b, v163
	v_mul_f32_e32 v178, 0xbfb8aa3b, v164
	v_mul_f32_e32 v180, 0xbfb8aa3b, v165
	v_mul_f32_e32 v182, 0xbfb8aa3b, v166
	v_mul_f32_e32 v184, 0xbfb8aa3b, v167
	v_pk_mul_f32 v[124:125], v[128:129], v[124:125]
	v_pk_mul_f32 v[126:127], v[130:131], v[126:127]
	v_pk_mul_f32 v[116:117], v[120:121], v[116:117]
	v_pk_mul_f32 v[118:119], v[122:123], v[118:119]
	v_pk_mul_f32 v[128:129], v[128:129], v[170:171] op_sel_hi:[1,0]
	v_pk_mul_f32 v[130:131], v[130:131], v[170:171] op_sel_hi:[1,0]
	v_pk_mul_f32 v[120:121], v[120:121], v[170:171] op_sel_hi:[1,0]
	v_pk_mul_f32 v[122:123], v[122:123], v[170:171] op_sel_hi:[1,0]
	v_exp_f32_e32 v128, v128
	v_exp_f32_e32 v129, v129
	v_exp_f32_e32 v130, v130
	v_exp_f32_e32 v131, v131
	v_exp_f32_e32 v120, v120
	v_exp_f32_e32 v121, v121
	v_exp_f32_e32 v122, v122
	v_exp_f32_e32 v123, v123
	v_pk_fma_f32 v[128:129], v[128:129], v[206:207], v[206:207] op_sel_hi:[1,0,0]
	v_pk_fma_f32 v[130:131], v[130:131], v[206:207], v[206:207] op_sel_hi:[1,0,0]
	v_pk_fma_f32 v[120:121], v[120:121], v[206:207], v[206:207] op_sel_hi:[1,0,0]
	v_pk_fma_f32 v[122:123], v[122:123], v[206:207], v[206:207] op_sel_hi:[1,0,0]
	v_rcp_f32_e32 v128, v128
	v_rcp_f32_e32 v129, v129
	v_rcp_f32_e32 v130, v130
	v_rcp_f32_e32 v131, v131
	v_rcp_f32_e32 v120, v120
	v_rcp_f32_e32 v121, v121
	v_rcp_f32_e32 v122, v122
	v_rcp_f32_e32 v123, v123
	v_pk_mul_f32 v[124:125], v[124:125], v[128:129]
	v_pk_mul_f32 v[126:127], v[126:127], v[130:131]
	v_pk_mul_f32 v[116:117], v[116:117], v[120:121]
	v_pk_mul_f32 v[118:119], v[118:119], v[122:123]
	v_cvt_pk_bf16_f32 v120, v124, v125
	v_cvt_pk_bf16_f32 v121, v126, v127
	v_cvt_pk_bf16_f32 v122, v116, v117
	v_cvt_pk_bf16_f32 v123, v118, v119
	ds_bpermute_b32 v128, v148, v120
	ds_bpermute_b32 v129, v148, v121
	ds_bpermute_b32 v130, v148, v122
	ds_bpermute_b32 v131, v148, v123
	v_pk_mul_f32 v[108:109], v[112:113], v[108:109]
	v_pk_mul_f32 v[110:111], v[114:115], v[110:111]
	v_pk_mul_f32 v[100:101], v[104:105], v[100:101]
	v_pk_mul_f32 v[102:103], v[106:107], v[102:103]
	v_pk_mul_f32 v[112:113], v[112:113], v[172:173] op_sel_hi:[1,0]
	v_pk_mul_f32 v[114:115], v[114:115], v[172:173] op_sel_hi:[1,0]
	v_pk_mul_f32 v[104:105], v[104:105], v[172:173] op_sel_hi:[1,0]
	v_pk_mul_f32 v[106:107], v[106:107], v[172:173] op_sel_hi:[1,0]
	v_exp_f32_e32 v112, v112
	v_exp_f32_e32 v113, v113
	v_exp_f32_e32 v114, v114
	v_exp_f32_e32 v115, v115
	v_exp_f32_e32 v104, v104
	v_exp_f32_e32 v105, v105
	v_exp_f32_e32 v106, v106
	v_exp_f32_e32 v107, v107
	v_pk_fma_f32 v[112:113], v[112:113], v[208:209], v[208:209] op_sel_hi:[1,0,0]
	v_pk_fma_f32 v[114:115], v[114:115], v[208:209], v[208:209] op_sel_hi:[1,0,0]
	v_pk_fma_f32 v[104:105], v[104:105], v[208:209], v[208:209] op_sel_hi:[1,0,0]
	v_pk_fma_f32 v[106:107], v[106:107], v[208:209], v[208:209] op_sel_hi:[1,0,0]
	v_rcp_f32_e32 v112, v112
	v_rcp_f32_e32 v113, v113
	v_rcp_f32_e32 v114, v114
	v_rcp_f32_e32 v115, v115
	v_rcp_f32_e32 v104, v104
	v_rcp_f32_e32 v105, v105
	v_rcp_f32_e32 v106, v106
	v_rcp_f32_e32 v107, v107
	v_pk_mul_f32 v[108:109], v[108:109], v[112:113]
	v_pk_mul_f32 v[110:111], v[110:111], v[114:115]
	v_pk_mul_f32 v[100:101], v[100:101], v[104:105]
	v_pk_mul_f32 v[102:103], v[102:103], v[106:107]
	v_cvt_pk_bf16_f32 v104, v108, v109
	v_cvt_pk_bf16_f32 v105, v110, v111
	v_cvt_pk_bf16_f32 v106, v100, v101
	v_cvt_pk_bf16_f32 v107, v102, v103
	s_waitcnt lgkmcnt(0)
	global_store_dwordx4 v[192:193], v[128:131], off
	v_lshl_add_u64 v[192:193], v[192:193], 0, s[28:29]
	ds_bpermute_b32 v112, v148, v104
	ds_bpermute_b32 v113, v148, v105
	ds_bpermute_b32 v114, v148, v106
	ds_bpermute_b32 v115, v148, v107
	v_pk_mul_f32 v[92:93], v[96:97], v[92:93]
	v_pk_mul_f32 v[94:95], v[98:99], v[94:95]
	v_pk_mul_f32 v[84:85], v[88:89], v[84:85]
	v_pk_mul_f32 v[86:87], v[90:91], v[86:87]
	v_pk_mul_f32 v[96:97], v[96:97], v[174:175] op_sel_hi:[1,0]
	v_pk_mul_f32 v[98:99], v[98:99], v[174:175] op_sel_hi:[1,0]
	v_pk_mul_f32 v[88:89], v[88:89], v[174:175] op_sel_hi:[1,0]
	v_pk_mul_f32 v[90:91], v[90:91], v[174:175] op_sel_hi:[1,0]
	v_exp_f32_e32 v96, v96
	v_exp_f32_e32 v97, v97
	v_exp_f32_e32 v98, v98
	v_exp_f32_e32 v99, v99
	v_exp_f32_e32 v88, v88
	v_exp_f32_e32 v89, v89
	v_exp_f32_e32 v90, v90
	v_exp_f32_e32 v91, v91
	v_pk_fma_f32 v[96:97], v[96:97], v[210:211], v[210:211] op_sel_hi:[1,0,0]
	v_pk_fma_f32 v[98:99], v[98:99], v[210:211], v[210:211] op_sel_hi:[1,0,0]
	v_pk_fma_f32 v[88:89], v[88:89], v[210:211], v[210:211] op_sel_hi:[1,0,0]
	v_pk_fma_f32 v[90:91], v[90:91], v[210:211], v[210:211] op_sel_hi:[1,0,0]
	v_rcp_f32_e32 v96, v96
	v_rcp_f32_e32 v97, v97
	v_rcp_f32_e32 v98, v98
	v_rcp_f32_e32 v99, v99
	v_rcp_f32_e32 v88, v88
	v_rcp_f32_e32 v89, v89
	v_rcp_f32_e32 v90, v90
	v_rcp_f32_e32 v91, v91
	v_pk_mul_f32 v[92:93], v[92:93], v[96:97]
	v_pk_mul_f32 v[94:95], v[94:95], v[98:99]
	v_pk_mul_f32 v[84:85], v[84:85], v[88:89]
	v_pk_mul_f32 v[86:87], v[86:87], v[90:91]
	v_cvt_pk_bf16_f32 v88, v92, v93
	v_cvt_pk_bf16_f32 v89, v94, v95
	v_cvt_pk_bf16_f32 v90, v84, v85
	v_cvt_pk_bf16_f32 v91, v86, v87
	s_waitcnt lgkmcnt(0)
	global_store_dwordx4 v[192:193], v[112:115], off
	v_lshl_add_u64 v[192:193], v[192:193], 0, s[28:29]
	ds_bpermute_b32 v96, v148, v88
	ds_bpermute_b32 v97, v148, v89
	ds_bpermute_b32 v98, v148, v90
	ds_bpermute_b32 v99, v148, v91
	v_pk_mul_f32 v[76:77], v[80:81], v[76:77]
	v_pk_mul_f32 v[78:79], v[82:83], v[78:79]
	v_pk_mul_f32 v[68:69], v[72:73], v[68:69]
	v_pk_mul_f32 v[70:71], v[74:75], v[70:71]
	v_pk_mul_f32 v[80:81], v[80:81], v[176:177] op_sel_hi:[1,0]
	v_pk_mul_f32 v[82:83], v[82:83], v[176:177] op_sel_hi:[1,0]
	v_pk_mul_f32 v[72:73], v[72:73], v[176:177] op_sel_hi:[1,0]
	v_pk_mul_f32 v[74:75], v[74:75], v[176:177] op_sel_hi:[1,0]
	v_exp_f32_e32 v80, v80
	v_exp_f32_e32 v81, v81
	v_exp_f32_e32 v82, v82
	v_exp_f32_e32 v83, v83
	v_exp_f32_e32 v72, v72
	v_exp_f32_e32 v73, v73
	v_exp_f32_e32 v74, v74
	v_exp_f32_e32 v75, v75
	v_pk_fma_f32 v[80:81], v[80:81], v[212:213], v[212:213] op_sel_hi:[1,0,0]
	v_pk_fma_f32 v[82:83], v[82:83], v[212:213], v[212:213] op_sel_hi:[1,0,0]
	v_pk_fma_f32 v[72:73], v[72:73], v[212:213], v[212:213] op_sel_hi:[1,0,0]
	v_pk_fma_f32 v[74:75], v[74:75], v[212:213], v[212:213] op_sel_hi:[1,0,0]
	v_rcp_f32_e32 v80, v80
	v_rcp_f32_e32 v81, v81
	v_rcp_f32_e32 v82, v82
	v_rcp_f32_e32 v83, v83
	v_rcp_f32_e32 v72, v72
	v_rcp_f32_e32 v73, v73
	v_rcp_f32_e32 v74, v74
	v_rcp_f32_e32 v75, v75
	v_pk_mul_f32 v[76:77], v[76:77], v[80:81]
	v_pk_mul_f32 v[78:79], v[78:79], v[82:83]
	v_pk_mul_f32 v[68:69], v[68:69], v[72:73]
	v_pk_mul_f32 v[70:71], v[70:71], v[74:75]
	v_cvt_pk_bf16_f32 v72, v76, v77
	v_cvt_pk_bf16_f32 v73, v78, v79
	v_cvt_pk_bf16_f32 v74, v68, v69
	v_cvt_pk_bf16_f32 v75, v70, v71
	s_waitcnt lgkmcnt(0)
	global_store_dwordx4 v[192:193], v[96:99], off
	v_lshl_add_u64 v[192:193], v[192:193], 0, s[28:29]
	ds_bpermute_b32 v80, v148, v72
	ds_bpermute_b32 v81, v148, v73
	ds_bpermute_b32 v82, v148, v74
	ds_bpermute_b32 v83, v148, v75
	v_pk_mul_f32 v[60:61], v[64:65], v[60:61]
	v_pk_mul_f32 v[62:63], v[66:67], v[62:63]
	v_pk_mul_f32 v[52:53], v[56:57], v[52:53]
	v_pk_mul_f32 v[54:55], v[58:59], v[54:55]
	v_pk_mul_f32 v[64:65], v[64:65], v[178:179] op_sel_hi:[1,0]
	v_pk_mul_f32 v[66:67], v[66:67], v[178:179] op_sel_hi:[1,0]
	v_pk_mul_f32 v[56:57], v[56:57], v[178:179] op_sel_hi:[1,0]
	v_pk_mul_f32 v[58:59], v[58:59], v[178:179] op_sel_hi:[1,0]
	v_exp_f32_e32 v64, v64
	v_exp_f32_e32 v65, v65
	v_exp_f32_e32 v66, v66
	v_exp_f32_e32 v67, v67
	v_exp_f32_e32 v56, v56
	v_exp_f32_e32 v57, v57
	v_exp_f32_e32 v58, v58
	v_exp_f32_e32 v59, v59
	v_pk_fma_f32 v[64:65], v[64:65], v[214:215], v[214:215] op_sel_hi:[1,0,0]
	v_pk_fma_f32 v[66:67], v[66:67], v[214:215], v[214:215] op_sel_hi:[1,0,0]
	v_pk_fma_f32 v[56:57], v[56:57], v[214:215], v[214:215] op_sel_hi:[1,0,0]
	v_pk_fma_f32 v[58:59], v[58:59], v[214:215], v[214:215] op_sel_hi:[1,0,0]
	v_rcp_f32_e32 v64, v64
	v_rcp_f32_e32 v65, v65
	v_rcp_f32_e32 v66, v66
	v_rcp_f32_e32 v67, v67
	v_rcp_f32_e32 v56, v56
	v_rcp_f32_e32 v57, v57
	v_rcp_f32_e32 v58, v58
	v_rcp_f32_e32 v59, v59
	v_pk_mul_f32 v[60:61], v[60:61], v[64:65]
	v_pk_mul_f32 v[62:63], v[62:63], v[66:67]
	v_pk_mul_f32 v[52:53], v[52:53], v[56:57]
	v_pk_mul_f32 v[54:55], v[54:55], v[58:59]
	v_cvt_pk_bf16_f32 v56, v60, v61
	v_cvt_pk_bf16_f32 v57, v62, v63
	v_cvt_pk_bf16_f32 v58, v52, v53
	v_cvt_pk_bf16_f32 v59, v54, v55
	s_waitcnt lgkmcnt(0)
	global_store_dwordx4 v[192:193], v[80:83], off
	s_mov_b32 s28, 0x6e000
	s_nop 0
	v_lshl_add_u64 v[192:193], v[192:193], 0, s[28:29]
	s_mov_b32 s28, 0x16000
	ds_bpermute_b32 v64, v148, v56
	ds_bpermute_b32 v65, v148, v57
	ds_bpermute_b32 v66, v148, v58
	ds_bpermute_b32 v67, v148, v59
	v_pk_mul_f32 v[44:45], v[48:49], v[44:45]
	v_pk_mul_f32 v[46:47], v[50:51], v[46:47]
	v_pk_mul_f32 v[36:37], v[40:41], v[36:37]
	v_pk_mul_f32 v[38:39], v[42:43], v[38:39]
	v_pk_mul_f32 v[48:49], v[48:49], v[180:181] op_sel_hi:[1,0]
	v_pk_mul_f32 v[50:51], v[50:51], v[180:181] op_sel_hi:[1,0]
	v_pk_mul_f32 v[40:41], v[40:41], v[180:181] op_sel_hi:[1,0]
	v_pk_mul_f32 v[42:43], v[42:43], v[180:181] op_sel_hi:[1,0]
	v_exp_f32_e32 v48, v48
	v_exp_f32_e32 v49, v49
	v_exp_f32_e32 v50, v50
	v_exp_f32_e32 v51, v51
	v_exp_f32_e32 v40, v40
	v_exp_f32_e32 v41, v41
	v_exp_f32_e32 v42, v42
	v_exp_f32_e32 v43, v43
	v_pk_fma_f32 v[48:49], v[48:49], v[216:217], v[216:217] op_sel_hi:[1,0,0]
	v_pk_fma_f32 v[50:51], v[50:51], v[216:217], v[216:217] op_sel_hi:[1,0,0]
	v_pk_fma_f32 v[40:41], v[40:41], v[216:217], v[216:217] op_sel_hi:[1,0,0]
	v_pk_fma_f32 v[42:43], v[42:43], v[216:217], v[216:217] op_sel_hi:[1,0,0]
	v_rcp_f32_e32 v48, v48
	v_rcp_f32_e32 v49, v49
	v_rcp_f32_e32 v50, v50
	v_rcp_f32_e32 v51, v51
	v_rcp_f32_e32 v40, v40
	v_rcp_f32_e32 v41, v41
	v_rcp_f32_e32 v42, v42
	v_rcp_f32_e32 v43, v43
	v_pk_mul_f32 v[44:45], v[44:45], v[48:49]
	v_pk_mul_f32 v[46:47], v[46:47], v[50:51]
	v_pk_mul_f32 v[36:37], v[36:37], v[40:41]
	v_pk_mul_f32 v[38:39], v[38:39], v[42:43]
	v_cvt_pk_bf16_f32 v40, v44, v45
	v_cvt_pk_bf16_f32 v41, v46, v47
	v_cvt_pk_bf16_f32 v42, v36, v37
	v_cvt_pk_bf16_f32 v43, v38, v39
	s_waitcnt lgkmcnt(0)
	global_store_dwordx4 v[192:193], v[64:67], off
	v_lshl_add_u64 v[192:193], v[192:193], 0, s[28:29]
	ds_bpermute_b32 v48, v148, v40
	ds_bpermute_b32 v49, v148, v41
	ds_bpermute_b32 v50, v148, v42
	ds_bpermute_b32 v51, v148, v43
	v_pk_mul_f32 v[28:29], v[32:33], v[28:29]
	v_pk_mul_f32 v[30:31], v[34:35], v[30:31]
	v_pk_mul_f32 v[20:21], v[24:25], v[20:21]
	v_pk_mul_f32 v[22:23], v[26:27], v[22:23]
	v_pk_mul_f32 v[32:33], v[32:33], v[182:183] op_sel_hi:[1,0]
	v_pk_mul_f32 v[34:35], v[34:35], v[182:183] op_sel_hi:[1,0]
	v_pk_mul_f32 v[24:25], v[24:25], v[182:183] op_sel_hi:[1,0]
	v_pk_mul_f32 v[26:27], v[26:27], v[182:183] op_sel_hi:[1,0]
	v_exp_f32_e32 v32, v32
	v_exp_f32_e32 v33, v33
	v_exp_f32_e32 v34, v34
	v_exp_f32_e32 v35, v35
	v_exp_f32_e32 v24, v24
	v_exp_f32_e32 v25, v25
	v_exp_f32_e32 v26, v26
	v_exp_f32_e32 v27, v27
	v_pk_fma_f32 v[32:33], v[32:33], v[218:219], v[218:219] op_sel_hi:[1,0,0]
	v_pk_fma_f32 v[34:35], v[34:35], v[218:219], v[218:219] op_sel_hi:[1,0,0]
	v_pk_fma_f32 v[24:25], v[24:25], v[218:219], v[218:219] op_sel_hi:[1,0,0]
	v_pk_fma_f32 v[26:27], v[26:27], v[218:219], v[218:219] op_sel_hi:[1,0,0]
	v_rcp_f32_e32 v32, v32
	v_rcp_f32_e32 v33, v33
	v_rcp_f32_e32 v34, v34
	v_rcp_f32_e32 v35, v35
	v_rcp_f32_e32 v24, v24
	v_rcp_f32_e32 v25, v25
	v_rcp_f32_e32 v26, v26
	v_rcp_f32_e32 v27, v27
	v_pk_mul_f32 v[28:29], v[28:29], v[32:33]
	v_pk_mul_f32 v[30:31], v[30:31], v[34:35]
	v_pk_mul_f32 v[20:21], v[20:21], v[24:25]
	v_pk_mul_f32 v[22:23], v[22:23], v[26:27]
	v_cvt_pk_bf16_f32 v24, v28, v29
	v_cvt_pk_bf16_f32 v25, v30, v31
	v_cvt_pk_bf16_f32 v26, v20, v21
	v_cvt_pk_bf16_f32 v27, v22, v23
	s_waitcnt lgkmcnt(0)
	global_store_dwordx4 v[192:193], v[48:51], off
	v_lshl_add_u64 v[192:193], v[192:193], 0, s[28:29]
	ds_bpermute_b32 v32, v148, v24
	ds_bpermute_b32 v33, v148, v25
	ds_bpermute_b32 v34, v148, v26
	ds_bpermute_b32 v35, v148, v27
	v_pk_mul_f32 v[12:13], v[16:17], v[12:13]
	v_pk_mul_f32 v[14:15], v[18:19], v[14:15]
	v_pk_mul_f32 v[4:5], v[8:9], v[4:5]
	v_pk_mul_f32 v[6:7], v[10:11], v[6:7]
	v_pk_mul_f32 v[16:17], v[16:17], v[184:185] op_sel_hi:[1,0]
	v_pk_mul_f32 v[18:19], v[18:19], v[184:185] op_sel_hi:[1,0]
	v_pk_mul_f32 v[8:9], v[8:9], v[184:185] op_sel_hi:[1,0]
	v_pk_mul_f32 v[10:11], v[10:11], v[184:185] op_sel_hi:[1,0]
	v_exp_f32_e32 v16, v16
	v_exp_f32_e32 v17, v17
	v_exp_f32_e32 v18, v18
	v_exp_f32_e32 v19, v19
	v_exp_f32_e32 v8, v8
	v_exp_f32_e32 v9, v9
	v_exp_f32_e32 v10, v10
	v_exp_f32_e32 v11, v11
	v_pk_fma_f32 v[16:17], v[16:17], v[220:221], v[220:221] op_sel_hi:[1,0,0]
	v_pk_fma_f32 v[18:19], v[18:19], v[220:221], v[220:221] op_sel_hi:[1,0,0]
	v_pk_fma_f32 v[8:9], v[8:9], v[220:221], v[220:221] op_sel_hi:[1,0,0]
	v_pk_fma_f32 v[10:11], v[10:11], v[220:221], v[220:221] op_sel_hi:[1,0,0]
	v_rcp_f32_e32 v16, v16
	v_rcp_f32_e32 v17, v17
	v_rcp_f32_e32 v18, v18
	v_rcp_f32_e32 v19, v19
	v_rcp_f32_e32 v8, v8
	v_rcp_f32_e32 v9, v9
	v_rcp_f32_e32 v10, v10
	v_rcp_f32_e32 v11, v11
	v_pk_mul_f32 v[12:13], v[12:13], v[16:17]
	v_pk_mul_f32 v[14:15], v[14:15], v[18:19]
	v_pk_mul_f32 v[4:5], v[4:5], v[8:9]
	v_pk_mul_f32 v[6:7], v[6:7], v[10:11]
	v_cvt_pk_bf16_f32 v8, v12, v13
	v_cvt_pk_bf16_f32 v9, v14, v15
	v_cvt_pk_bf16_f32 v10, v4, v5
	v_cvt_pk_bf16_f32 v11, v6, v7
	s_waitcnt lgkmcnt(0)
	global_store_dwordx4 v[192:193], v[32:35], off
	v_lshl_add_u64 v[192:193], v[192:193], 0, s[28:29]
	ds_bpermute_b32 v16, v148, v8
	ds_bpermute_b32 v17, v148, v9
	ds_bpermute_b32 v18, v148, v10
	ds_bpermute_b32 v19, v148, v11
	s_andn2_b64 vcc, exec, s[38:39]
	s_mov_b64 s[28:29], -1
	s_waitcnt lgkmcnt(0)
	global_store_dwordx4 v[192:193], v[16:19], off
	s_cbranch_vccnz .LBB0_308
	s_andn2_b64 vcc, exec, s[14:15]
	s_cbranch_vccnz .LBB0_307
	s_barrier
	s_branch .LBB0_307
